# k29: k28 + in-projection epilogue q/k norm row sums via v_permlane16/32_swap instead of ds_bpermute
# baseline (speedup 1.0000x reference)
;     __device__ __forceinline__ void operator()(const f32x4 (&acc)[2][2][4][2], const pg8::Unit& u, int wr, int wc, int fr, int fq) const {
;     ...
;                 if (type == 2 || type == 3) {
;                     float ss = 0.f;
; #pragma unroll
;                     for (int bj = 0; bj < 2; ++bj)
; #pragma unroll
;                         for (int e = 0; e < 8; ++e) ss += v[bj][e] * v[bj][e];
;                     ss += __shfl_xor(ss, 16); ss += __shfl_xor(ss, 32);
;                     const float rs = rsqrtf(ss * (1.f / 64.f) + NORM_EPS);
; #pragma unroll
;                     for (int bj = 0; bj < 2; ++bj)
; #pragma unroll
;                         for (int e = 0; e < 8; ++e) v[bj][e] = v[bj][e] * rs * gg[bj][e];
.LBB0_285:
	s_andn2_b64 vcc, exec, s[0:1]
	s_cbranch_vccnz .LBB0_287
	v_mul_f32_e32 v132, v125, v125
	v_fmac_f32_e32 v132, v124, v124
	v_fmac_f32_e32 v132, v126, v126
	v_fmac_f32_e32 v132, v127, v127
	v_fmac_f32_e32 v132, v120, v120
	v_fmac_f32_e32 v132, v121, v121
	v_fmac_f32_e32 v132, v122, v122
	v_fmac_f32_e32 v132, v123, v123
	v_pk_mul_f32 v[130:131], v[116:117], v[116:117]
	v_pk_mul_f32 v[128:129], v[118:119], v[118:119]
	v_add_f32_e32 v130, v132, v130
	v_add_f32_e32 v130, v131, v130
	v_add_f32_e32 v128, v128, v130
	v_add_f32_e32 v132, v129, v128
	v_pk_mul_f32 v[130:131], v[112:113], v[112:113]
	v_pk_mul_f32 v[128:129], v[114:115], v[114:115]
	v_add_f32_e32 v130, v130, v132
	v_add_f32_e32 v130, v131, v130
	v_add_f32_e32 v128, v128, v130
	v_and_b32_e32 v130, 64, v195
	v_add_f32_e32 v128, v129, v128
	v_xor_b32_e32 v129, 16, v195
	v_add_u32_e32 v130, 64, v130
	v_cmp_lt_i32_e32 vcc, v129, v130
	s_nop 1
	v_cndmask_b32_e32 v129, v195, v129, vcc
	v_lshlrev_b32_e32 v129, 2, v129
	v_mov_b32_e32 v129, v128
	s_nop 1
	v_permlane16_swap_b32_e32 v129, v128
	s_nop 1
	s_waitcnt lgkmcnt(0)
	v_add_f32_e32 v128, v128, v129
	v_xor_b32_e32 v129, 32, v195
	v_cmp_lt_i32_e32 vcc, v129, v130
	s_nop 1
	v_cndmask_b32_e32 v129, v195, v129, vcc
	v_lshlrev_b32_e32 v129, 2, v129
	v_mov_b32_e32 v129, v128
	s_nop 1
	v_permlane32_swap_b32_e32 v129, v128
	s_nop 1
	s_waitcnt lgkmcnt(0)
	v_add_f32_e32 v128, v128, v129
	v_fmamk_f32 v128, v128, 0x3c800000, v193
	v_mul_f32_e32 v129, 0x4b800000, v128
	v_cmp_gt_f32_e32 vcc, s35, v128
	s_nop 1
	v_cndmask_b32_e32 v128, v128, v129, vcc
	v_rsq_f32_e32 v128, v128
	s_nop 0
	v_mul_f32_e32 v129, 0x45800000, v128
	v_cndmask_b32_e32 v142, v128, v129, vcc
	v_pk_mul_f32 v[124:125], v[124:125], v[142:143] op_sel_hi:[1,0]
	v_pk_mul_f32 v[120:121], v[120:121], v[142:143] op_sel_hi:[1,0]
	v_pk_mul_f32 v[116:117], v[116:117], v[142:143] op_sel_hi:[1,0]
	v_pk_mul_f32 v[112:113], v[112:113], v[142:143] op_sel_hi:[1,0]
	v_pk_mul_f32 v[128:129], v[186:187], v[124:125]
	v_pk_mul_f32 v[124:125], v[126:127], v[142:143] op_sel_hi:[1,0]
	v_pk_mul_f32 v[132:133], v[188:189], v[120:121]
	v_pk_mul_f32 v[120:121], v[122:123], v[142:143] op_sel_hi:[1,0]
	v_pk_mul_f32 v[136:137], v[174:175], v[116:117]
	v_pk_mul_f32 v[116:117], v[118:119], v[142:143] op_sel_hi:[1,0]
	v_pk_mul_f32 v[140:141], v[178:179], v[112:113]
	v_pk_mul_f32 v[112:113], v[114:115], v[142:143] op_sel_hi:[1,0]
	v_pk_mul_f32 v[130:131], v[182:183], v[124:125]
	v_pk_mul_f32 v[134:135], v[184:185], v[120:121]
	v_pk_mul_f32 v[138:139], v[176:177], v[116:117]
	v_pk_mul_f32 v[142:143], v[180:181], v[112:113]

;     __device__ __forceinline__ void operator()(const f32x4 (&acc)[2][2][4][2], const pg8::Unit& u, int wr, int wc, int fr, int fq) const {
;     ...
;                 if (type == 2 || type == 3) {
;                     float ss = 0.f;
; #pragma unroll
;                     for (int bj = 0; bj < 2; ++bj)
; #pragma unroll
;                         for (int e = 0; e < 8; ++e) ss += v[bj][e] * v[bj][e];
;                     ss += __shfl_xor(ss, 16); ss += __shfl_xor(ss, 32);
;                     const float rs = rsqrtf(ss * (1.f / 64.f) + NORM_EPS);
; #pragma unroll
;                     for (int bj = 0; bj < 2; ++bj)
; #pragma unroll
;                         for (int e = 0; e < 8; ++e) v[bj][e] = v[bj][e] * rs * gg[bj][e];
.LBB0_318:
	s_andn2_b64 vcc, exec, s[10:11]
	s_cbranch_vccnz .LBB0_320
	v_mul_f32_e32 v116, v109, v109
	v_fmac_f32_e32 v116, v108, v108
	v_fmac_f32_e32 v116, v110, v110
	v_fmac_f32_e32 v116, v111, v111
	v_fmac_f32_e32 v116, v104, v104
	v_fmac_f32_e32 v116, v105, v105
	v_fmac_f32_e32 v116, v106, v106
	v_fmac_f32_e32 v116, v107, v107
	v_pk_mul_f32 v[114:115], v[100:101], v[100:101]
	v_pk_mul_f32 v[112:113], v[102:103], v[102:103]
	v_add_f32_e32 v114, v116, v114
	v_add_f32_e32 v114, v115, v114
	v_add_f32_e32 v112, v112, v114
	v_add_f32_e32 v116, v113, v112
	v_pk_mul_f32 v[114:115], v[96:97], v[96:97]
	v_pk_mul_f32 v[112:113], v[98:99], v[98:99]
	v_add_f32_e32 v114, v114, v116
	v_add_f32_e32 v114, v115, v114
	v_add_f32_e32 v112, v112, v114
	v_and_b32_e32 v114, 64, v195
	v_add_f32_e32 v112, v113, v112
	v_xor_b32_e32 v113, 16, v195
	v_add_u32_e32 v114, 64, v114
	v_cmp_lt_i32_e32 vcc, v113, v114
	s_nop 1
	v_cndmask_b32_e32 v113, v195, v113, vcc
	v_lshlrev_b32_e32 v113, 2, v113
	v_mov_b32_e32 v113, v112
	s_nop 1
	v_permlane16_swap_b32_e32 v113, v112
	s_nop 1
	s_waitcnt lgkmcnt(0)
	v_add_f32_e32 v112, v112, v113
	v_xor_b32_e32 v113, 32, v195
	v_cmp_lt_i32_e32 vcc, v113, v114
	s_nop 1
	v_cndmask_b32_e32 v113, v195, v113, vcc
	v_lshlrev_b32_e32 v113, 2, v113
	v_mov_b32_e32 v113, v112
	s_nop 1
	v_permlane32_swap_b32_e32 v113, v112
	s_nop 1
	s_waitcnt lgkmcnt(0)
	v_add_f32_e32 v112, v112, v113
	v_fmamk_f32 v112, v112, 0x3c800000, v193
	v_mul_f32_e32 v113, 0x4b800000, v112
	v_cmp_gt_f32_e32 vcc, s35, v112
	s_nop 1
	v_cndmask_b32_e32 v112, v112, v113, vcc
	v_rsq_f32_e32 v112, v112
	s_nop 0
	v_mul_f32_e32 v113, 0x45800000, v112
	v_cndmask_b32_e32 v126, v112, v113, vcc
	v_pk_mul_f32 v[108:109], v[108:109], v[126:127] op_sel_hi:[1,0]
	v_pk_mul_f32 v[104:105], v[104:105], v[126:127] op_sel_hi:[1,0]
	v_pk_mul_f32 v[100:101], v[100:101], v[126:127] op_sel_hi:[1,0]
	v_pk_mul_f32 v[96:97], v[96:97], v[126:127] op_sel_hi:[1,0]
	v_pk_mul_f32 v[112:113], v[186:187], v[108:109]
	v_pk_mul_f32 v[108:109], v[110:111], v[126:127] op_sel_hi:[1,0]
	v_pk_mul_f32 v[116:117], v[188:189], v[104:105]
	v_pk_mul_f32 v[104:105], v[106:107], v[126:127] op_sel_hi:[1,0]
	v_pk_mul_f32 v[120:121], v[174:175], v[100:101]
	v_pk_mul_f32 v[100:101], v[102:103], v[126:127] op_sel_hi:[1,0]
	v_pk_mul_f32 v[124:125], v[178:179], v[96:97]
	v_pk_mul_f32 v[96:97], v[98:99], v[126:127] op_sel_hi:[1,0]
	v_pk_mul_f32 v[114:115], v[182:183], v[108:109]
	v_pk_mul_f32 v[118:119], v[184:185], v[104:105]
	v_pk_mul_f32 v[122:123], v[176:177], v[100:101]
	v_pk_mul_f32 v[126:127], v[180:181], v[96:97]

;     __device__ __forceinline__ void operator()(const f32x4 (&acc)[2][2][4][2], const pg8::Unit& u, int wr, int wc, int fr, int fq) const {
;     ...
;                 if (type == 2 || type == 3) {
;                     float ss = 0.f;
; #pragma unroll
;                     for (int bj = 0; bj < 2; ++bj)
; #pragma unroll
;                         for (int e = 0; e < 8; ++e) ss += v[bj][e] * v[bj][e];
;                     ss += __shfl_xor(ss, 16); ss += __shfl_xor(ss, 32);
;                     const float rs = rsqrtf(ss * (1.f / 64.f) + NORM_EPS);
; #pragma unroll
;                     for (int bj = 0; bj < 2; ++bj)
; #pragma unroll
;                         for (int e = 0; e < 8; ++e) v[bj][e] = v[bj][e] * rs * gg[bj][e];
.LBB0_352:
	v_mul_f32_e32 v100, v93, v93
	v_fmac_f32_e32 v100, v92, v92
	v_fmac_f32_e32 v100, v94, v94
	v_fmac_f32_e32 v100, v95, v95
	v_fmac_f32_e32 v100, v88, v88
	v_fmac_f32_e32 v100, v89, v89
	v_fmac_f32_e32 v100, v90, v90
	v_fmac_f32_e32 v100, v91, v91
	v_pk_mul_f32 v[98:99], v[84:85], v[84:85]
	v_pk_mul_f32 v[96:97], v[86:87], v[86:87]
	v_add_f32_e32 v98, v100, v98
	v_add_f32_e32 v98, v99, v98
	v_add_f32_e32 v96, v96, v98
	v_add_f32_e32 v100, v97, v96
	v_pk_mul_f32 v[98:99], v[80:81], v[80:81]
	v_pk_mul_f32 v[96:97], v[82:83], v[82:83]
	v_add_f32_e32 v98, v98, v100
	v_add_f32_e32 v98, v99, v98
	v_add_f32_e32 v96, v96, v98
	v_and_b32_e32 v98, 64, v195
	v_add_f32_e32 v96, v97, v96
	v_xor_b32_e32 v97, 16, v195
	v_add_u32_e32 v98, 64, v98
	v_cmp_lt_i32_e32 vcc, v97, v98
	s_nop 1
	v_cndmask_b32_e32 v97, v195, v97, vcc
	v_lshlrev_b32_e32 v97, 2, v97
	v_mov_b32_e32 v97, v96
	s_nop 1
	v_permlane16_swap_b32_e32 v97, v96
	s_nop 1
	s_waitcnt lgkmcnt(0)
	v_add_f32_e32 v96, v96, v97
	v_xor_b32_e32 v97, 32, v195
	v_cmp_lt_i32_e32 vcc, v97, v98
	s_nop 1
	v_cndmask_b32_e32 v97, v195, v97, vcc
	v_lshlrev_b32_e32 v97, 2, v97
	v_mov_b32_e32 v97, v96
	s_nop 1
	v_permlane32_swap_b32_e32 v97, v96
	s_nop 1
	s_waitcnt lgkmcnt(0)
	v_add_f32_e32 v96, v96, v97
	v_fmamk_f32 v96, v96, 0x3c800000, v193
	v_mul_f32_e32 v97, 0x4b800000, v96
	v_cmp_gt_f32_e32 vcc, s35, v96
	s_nop 1
	v_cndmask_b32_e32 v96, v96, v97, vcc
	v_rsq_f32_e32 v96, v96
	s_nop 0
	v_mul_f32_e32 v97, 0x45800000, v96
	v_cndmask_b32_e32 v110, v96, v97, vcc
	v_pk_mul_f32 v[92:93], v[92:93], v[110:111] op_sel_hi:[1,0]
	v_pk_mul_f32 v[88:89], v[88:89], v[110:111] op_sel_hi:[1,0]
	v_pk_mul_f32 v[84:85], v[84:85], v[110:111] op_sel_hi:[1,0]
	v_pk_mul_f32 v[80:81], v[80:81], v[110:111] op_sel_hi:[1,0]
	v_pk_mul_f32 v[96:97], v[186:187], v[92:93]
	v_pk_mul_f32 v[92:93], v[94:95], v[110:111] op_sel_hi:[1,0]
	v_pk_mul_f32 v[100:101], v[188:189], v[88:89]
	v_pk_mul_f32 v[88:89], v[90:91], v[110:111] op_sel_hi:[1,0]
	v_pk_mul_f32 v[104:105], v[174:175], v[84:85]
	v_pk_mul_f32 v[84:85], v[86:87], v[110:111] op_sel_hi:[1,0]
	v_pk_mul_f32 v[108:109], v[178:179], v[80:81]
	v_pk_mul_f32 v[80:81], v[82:83], v[110:111] op_sel_hi:[1,0]
	v_pk_mul_f32 v[98:99], v[182:183], v[92:93]
	v_pk_mul_f32 v[102:103], v[184:185], v[88:89]
	v_pk_mul_f32 v[106:107], v[176:177], v[84:85]
	v_pk_mul_f32 v[110:111], v[180:181], v[80:81]

;     __device__ __forceinline__ void operator()(const f32x4 (&acc)[2][2][4][2], const pg8::Unit& u, int wr, int wc, int fr, int fq) const {
;     ...
;                 if (type == 2 || type == 3) {
;                     float ss = 0.f;
; #pragma unroll
;                     for (int bj = 0; bj < 2; ++bj)
; #pragma unroll
;                         for (int e = 0; e < 8; ++e) ss += v[bj][e] * v[bj][e];
;                     ss += __shfl_xor(ss, 16); ss += __shfl_xor(ss, 32);
;                     const float rs = rsqrtf(ss * (1.f / 64.f) + NORM_EPS);
; #pragma unroll
;                     for (int bj = 0; bj < 2; ++bj)
; #pragma unroll
;                         for (int e = 0; e < 8; ++e) v[bj][e] = v[bj][e] * rs * gg[bj][e];
.LBB0_385:
	v_mul_f32_e32 v84, v77, v77
	v_fmac_f32_e32 v84, v76, v76
	v_fmac_f32_e32 v84, v78, v78
	v_fmac_f32_e32 v84, v79, v79
	v_fmac_f32_e32 v84, v72, v72
	v_fmac_f32_e32 v84, v73, v73
	v_fmac_f32_e32 v84, v74, v74
	v_fmac_f32_e32 v84, v75, v75
	v_pk_mul_f32 v[82:83], v[68:69], v[68:69]
	v_pk_mul_f32 v[80:81], v[70:71], v[70:71]
	v_add_f32_e32 v82, v84, v82
	v_add_f32_e32 v82, v83, v82
	v_add_f32_e32 v80, v80, v82
	v_add_f32_e32 v84, v81, v80
	v_pk_mul_f32 v[82:83], v[64:65], v[64:65]
	v_pk_mul_f32 v[80:81], v[66:67], v[66:67]
	v_add_f32_e32 v82, v82, v84
	v_add_f32_e32 v82, v83, v82
	v_add_f32_e32 v80, v80, v82
	v_and_b32_e32 v82, 64, v195
	v_add_f32_e32 v80, v81, v80
	v_xor_b32_e32 v81, 16, v195
	v_add_u32_e32 v82, 64, v82
	v_cmp_lt_i32_e32 vcc, v81, v82
	s_nop 1
	v_cndmask_b32_e32 v81, v195, v81, vcc
	v_lshlrev_b32_e32 v81, 2, v81
	v_mov_b32_e32 v81, v80
	s_nop 1
	v_permlane16_swap_b32_e32 v81, v80
	s_nop 1
	s_waitcnt lgkmcnt(0)
	v_add_f32_e32 v80, v80, v81
	v_xor_b32_e32 v81, 32, v195
	v_cmp_lt_i32_e32 vcc, v81, v82
	s_nop 1
	v_cndmask_b32_e32 v81, v195, v81, vcc
	v_lshlrev_b32_e32 v81, 2, v81
	v_mov_b32_e32 v81, v80
	s_nop 1
	v_permlane32_swap_b32_e32 v81, v80
	s_nop 1
	s_waitcnt lgkmcnt(0)
	v_add_f32_e32 v80, v80, v81
	v_fmamk_f32 v80, v80, 0x3c800000, v193
	v_mul_f32_e32 v81, 0x4b800000, v80
	v_cmp_gt_f32_e32 vcc, s35, v80
	s_nop 1
	v_cndmask_b32_e32 v80, v80, v81, vcc
	v_rsq_f32_e32 v80, v80
	s_nop 0
	v_mul_f32_e32 v81, 0x45800000, v80
	v_cndmask_b32_e32 v94, v80, v81, vcc
	v_pk_mul_f32 v[76:77], v[76:77], v[94:95] op_sel_hi:[1,0]
	v_pk_mul_f32 v[72:73], v[72:73], v[94:95] op_sel_hi:[1,0]
	v_pk_mul_f32 v[68:69], v[68:69], v[94:95] op_sel_hi:[1,0]
	v_pk_mul_f32 v[64:65], v[64:65], v[94:95] op_sel_hi:[1,0]
	v_pk_mul_f32 v[80:81], v[186:187], v[76:77]
	v_pk_mul_f32 v[76:77], v[78:79], v[94:95] op_sel_hi:[1,0]
	v_pk_mul_f32 v[84:85], v[188:189], v[72:73]
	v_pk_mul_f32 v[72:73], v[74:75], v[94:95] op_sel_hi:[1,0]
	v_pk_mul_f32 v[88:89], v[174:175], v[68:69]
	v_pk_mul_f32 v[68:69], v[70:71], v[94:95] op_sel_hi:[1,0]
	v_pk_mul_f32 v[92:93], v[178:179], v[64:65]
	v_pk_mul_f32 v[64:65], v[66:67], v[94:95] op_sel_hi:[1,0]
	v_pk_mul_f32 v[82:83], v[182:183], v[76:77]
	v_pk_mul_f32 v[86:87], v[184:185], v[72:73]
	v_pk_mul_f32 v[90:91], v[176:177], v[68:69]
	v_pk_mul_f32 v[94:95], v[180:181], v[64:65]

;     __device__ __forceinline__ void operator()(const f32x4 (&acc)[2][2][4][2], const pg8::Unit& u, int wr, int wc, int fr, int fq) const {
;     ...
;                 if (type == 2 || type == 3) {
;                     float ss = 0.f;
; #pragma unroll
;                     for (int bj = 0; bj < 2; ++bj)
; #pragma unroll
;                         for (int e = 0; e < 8; ++e) ss += v[bj][e] * v[bj][e];
;                     ss += __shfl_xor(ss, 16); ss += __shfl_xor(ss, 32);
;                     const float rs = rsqrtf(ss * (1.f / 64.f) + NORM_EPS);
; #pragma unroll
;                     for (int bj = 0; bj < 2; ++bj)
; #pragma unroll
;                         for (int e = 0; e < 8; ++e) v[bj][e] = v[bj][e] * rs * gg[bj][e];
.LBB0_418:
	v_mul_f32_e32 v68, v61, v61
	v_fmac_f32_e32 v68, v60, v60
	v_fmac_f32_e32 v68, v62, v62
	v_fmac_f32_e32 v68, v63, v63
	v_fmac_f32_e32 v68, v56, v56
	v_fmac_f32_e32 v68, v57, v57
	v_fmac_f32_e32 v68, v58, v58
	v_fmac_f32_e32 v68, v59, v59
	v_pk_mul_f32 v[66:67], v[52:53], v[52:53]
	v_pk_mul_f32 v[64:65], v[54:55], v[54:55]
	v_add_f32_e32 v66, v68, v66
	v_add_f32_e32 v66, v67, v66
	v_add_f32_e32 v64, v64, v66
	v_add_f32_e32 v68, v65, v64
	v_pk_mul_f32 v[66:67], v[48:49], v[48:49]
	v_pk_mul_f32 v[64:65], v[50:51], v[50:51]
	v_add_f32_e32 v66, v66, v68
	v_add_f32_e32 v66, v67, v66
	v_add_f32_e32 v64, v64, v66
	v_and_b32_e32 v66, 64, v195
	v_add_f32_e32 v64, v65, v64
	v_xor_b32_e32 v65, 16, v195
	v_add_u32_e32 v66, 64, v66
	v_cmp_lt_i32_e32 vcc, v65, v66
	s_nop 1
	v_cndmask_b32_e32 v65, v195, v65, vcc
	v_lshlrev_b32_e32 v65, 2, v65
	v_mov_b32_e32 v65, v64
	s_nop 1
	v_permlane16_swap_b32_e32 v65, v64
	s_nop 1
	s_waitcnt lgkmcnt(0)
	v_add_f32_e32 v64, v64, v65
	v_xor_b32_e32 v65, 32, v195
	v_cmp_lt_i32_e32 vcc, v65, v66
	s_nop 1
	v_cndmask_b32_e32 v65, v195, v65, vcc
	v_lshlrev_b32_e32 v65, 2, v65
	v_mov_b32_e32 v65, v64
	s_nop 1
	v_permlane32_swap_b32_e32 v65, v64
	s_nop 1
	s_waitcnt lgkmcnt(0)
	v_add_f32_e32 v64, v64, v65
	v_fmamk_f32 v64, v64, 0x3c800000, v193
	v_mul_f32_e32 v65, 0x4b800000, v64
	v_cmp_gt_f32_e32 vcc, s35, v64
	s_nop 1
	v_cndmask_b32_e32 v64, v64, v65, vcc
	v_rsq_f32_e32 v64, v64
	s_nop 0
	v_mul_f32_e32 v65, 0x45800000, v64
	v_cndmask_b32_e32 v78, v64, v65, vcc
	v_pk_mul_f32 v[60:61], v[60:61], v[78:79] op_sel_hi:[1,0]
	v_pk_mul_f32 v[56:57], v[56:57], v[78:79] op_sel_hi:[1,0]
	v_pk_mul_f32 v[52:53], v[52:53], v[78:79] op_sel_hi:[1,0]
	v_pk_mul_f32 v[48:49], v[48:49], v[78:79] op_sel_hi:[1,0]
	v_pk_mul_f32 v[64:65], v[186:187], v[60:61]
	v_pk_mul_f32 v[60:61], v[62:63], v[78:79] op_sel_hi:[1,0]
	v_pk_mul_f32 v[68:69], v[188:189], v[56:57]
	v_pk_mul_f32 v[56:57], v[58:59], v[78:79] op_sel_hi:[1,0]
	v_pk_mul_f32 v[72:73], v[174:175], v[52:53]
	v_pk_mul_f32 v[52:53], v[54:55], v[78:79] op_sel_hi:[1,0]
	v_pk_mul_f32 v[76:77], v[178:179], v[48:49]
	v_pk_mul_f32 v[48:49], v[50:51], v[78:79] op_sel_hi:[1,0]
	v_pk_mul_f32 v[66:67], v[182:183], v[60:61]
	v_pk_mul_f32 v[70:71], v[184:185], v[56:57]
	v_pk_mul_f32 v[74:75], v[176:177], v[52:53]
	v_pk_mul_f32 v[78:79], v[180:181], v[48:49]

;     __device__ __forceinline__ void operator()(const f32x4 (&acc)[2][2][4][2], const pg8::Unit& u, int wr, int wc, int fr, int fq) const {
;     ...
;                 if (type == 2 || type == 3) {
;                     float ss = 0.f;
; #pragma unroll
;                     for (int bj = 0; bj < 2; ++bj)
; #pragma unroll
;                         for (int e = 0; e < 8; ++e) ss += v[bj][e] * v[bj][e];
;                     ss += __shfl_xor(ss, 16); ss += __shfl_xor(ss, 32);
;                     const float rs = rsqrtf(ss * (1.f / 64.f) + NORM_EPS);
; #pragma unroll
;                     for (int bj = 0; bj < 2; ++bj)
; #pragma unroll
;                         for (int e = 0; e < 8; ++e) v[bj][e] = v[bj][e] * rs * gg[bj][e];
.LBB0_451:
	v_mul_f32_e32 v52, v45, v45
	v_fmac_f32_e32 v52, v44, v44
	v_fmac_f32_e32 v52, v46, v46
	v_fmac_f32_e32 v52, v47, v47
	v_fmac_f32_e32 v52, v40, v40
	v_fmac_f32_e32 v52, v41, v41
	v_fmac_f32_e32 v52, v42, v42
	v_fmac_f32_e32 v52, v43, v43
	v_pk_mul_f32 v[50:51], v[36:37], v[36:37]
	v_pk_mul_f32 v[48:49], v[38:39], v[38:39]
	v_add_f32_e32 v50, v52, v50
	v_add_f32_e32 v50, v51, v50
	v_add_f32_e32 v48, v48, v50
	v_add_f32_e32 v52, v49, v48
	v_pk_mul_f32 v[50:51], v[32:33], v[32:33]
	v_pk_mul_f32 v[48:49], v[34:35], v[34:35]
	v_add_f32_e32 v50, v50, v52
	v_add_f32_e32 v50, v51, v50
	v_add_f32_e32 v48, v48, v50
	v_and_b32_e32 v50, 64, v195
	v_add_f32_e32 v48, v49, v48
	v_xor_b32_e32 v49, 16, v195
	v_add_u32_e32 v50, 64, v50
	v_cmp_lt_i32_e32 vcc, v49, v50
	s_nop 1
	v_cndmask_b32_e32 v49, v195, v49, vcc
	v_lshlrev_b32_e32 v49, 2, v49
	v_mov_b32_e32 v49, v48
	s_nop 1
	v_permlane16_swap_b32_e32 v49, v48
	s_nop 1
	s_waitcnt lgkmcnt(0)
	v_add_f32_e32 v48, v48, v49
	v_xor_b32_e32 v49, 32, v195
	v_cmp_lt_i32_e32 vcc, v49, v50
	s_nop 1
	v_cndmask_b32_e32 v49, v195, v49, vcc
	v_lshlrev_b32_e32 v49, 2, v49
	v_mov_b32_e32 v49, v48
	s_nop 1
	v_permlane32_swap_b32_e32 v49, v48
	s_nop 1
	s_waitcnt lgkmcnt(0)
	v_add_f32_e32 v48, v48, v49
	v_fmamk_f32 v48, v48, 0x3c800000, v193
	v_mul_f32_e32 v49, 0x4b800000, v48
	v_cmp_gt_f32_e32 vcc, s35, v48
	s_nop 1
	v_cndmask_b32_e32 v48, v48, v49, vcc
	v_rsq_f32_e32 v48, v48
	s_nop 0
	v_mul_f32_e32 v49, 0x45800000, v48
	v_cndmask_b32_e32 v62, v48, v49, vcc
	v_pk_mul_f32 v[44:45], v[44:45], v[62:63] op_sel_hi:[1,0]
	v_pk_mul_f32 v[40:41], v[40:41], v[62:63] op_sel_hi:[1,0]
	v_pk_mul_f32 v[36:37], v[36:37], v[62:63] op_sel_hi:[1,0]
	v_pk_mul_f32 v[32:33], v[32:33], v[62:63] op_sel_hi:[1,0]
	v_pk_mul_f32 v[48:49], v[186:187], v[44:45]
	v_pk_mul_f32 v[44:45], v[46:47], v[62:63] op_sel_hi:[1,0]
	v_pk_mul_f32 v[52:53], v[188:189], v[40:41]
	v_pk_mul_f32 v[40:41], v[42:43], v[62:63] op_sel_hi:[1,0]
	v_pk_mul_f32 v[56:57], v[174:175], v[36:37]
	v_pk_mul_f32 v[36:37], v[38:39], v[62:63] op_sel_hi:[1,0]
	v_pk_mul_f32 v[60:61], v[178:179], v[32:33]
	v_pk_mul_f32 v[32:33], v[34:35], v[62:63] op_sel_hi:[1,0]
	v_pk_mul_f32 v[50:51], v[182:183], v[44:45]
	v_pk_mul_f32 v[54:55], v[184:185], v[40:41]
	v_pk_mul_f32 v[58:59], v[176:177], v[36:37]
	v_pk_mul_f32 v[62:63], v[180:181], v[32:33]

;     __device__ __forceinline__ void operator()(const f32x4 (&acc)[2][2][4][2], const pg8::Unit& u, int wr, int wc, int fr, int fq) const {
;     ...
;                 if (type == 2 || type == 3) {
;                     float ss = 0.f;
; #pragma unroll
;                     for (int bj = 0; bj < 2; ++bj)
; #pragma unroll
;                         for (int e = 0; e < 8; ++e) ss += v[bj][e] * v[bj][e];
;                     ss += __shfl_xor(ss, 16); ss += __shfl_xor(ss, 32);
;                     const float rs = rsqrtf(ss * (1.f / 64.f) + NORM_EPS);
; #pragma unroll
;                     for (int bj = 0; bj < 2; ++bj)
; #pragma unroll
;                         for (int e = 0; e < 8; ++e) v[bj][e] = v[bj][e] * rs * gg[bj][e];
.LBB0_484:
	v_mul_f32_e32 v36, v29, v29
	v_fmac_f32_e32 v36, v28, v28
	v_fmac_f32_e32 v36, v30, v30
	v_fmac_f32_e32 v36, v31, v31
	v_fmac_f32_e32 v36, v24, v24
	v_fmac_f32_e32 v36, v25, v25
	v_fmac_f32_e32 v36, v26, v26
	v_fmac_f32_e32 v36, v27, v27
	v_pk_mul_f32 v[34:35], v[20:21], v[20:21]
	v_pk_mul_f32 v[32:33], v[22:23], v[22:23]
	v_add_f32_e32 v34, v36, v34
	v_add_f32_e32 v34, v35, v34
	v_add_f32_e32 v32, v32, v34
	v_add_f32_e32 v36, v33, v32
	v_pk_mul_f32 v[34:35], v[16:17], v[16:17]
	v_pk_mul_f32 v[32:33], v[18:19], v[18:19]
	v_add_f32_e32 v34, v34, v36
	v_add_f32_e32 v34, v35, v34
	v_add_f32_e32 v32, v32, v34
	v_and_b32_e32 v34, 64, v195
	v_add_f32_e32 v32, v33, v32
	v_xor_b32_e32 v33, 16, v195
	v_add_u32_e32 v34, 64, v34
	v_cmp_lt_i32_e32 vcc, v33, v34
	s_nop 1
	v_cndmask_b32_e32 v33, v195, v33, vcc
	v_lshlrev_b32_e32 v33, 2, v33
	v_mov_b32_e32 v33, v32
	s_nop 1
	v_permlane16_swap_b32_e32 v33, v32
	s_nop 1
	s_waitcnt lgkmcnt(0)
	v_add_f32_e32 v32, v32, v33
	v_xor_b32_e32 v33, 32, v195
	v_cmp_lt_i32_e32 vcc, v33, v34
	s_nop 1
	v_cndmask_b32_e32 v33, v195, v33, vcc
	v_lshlrev_b32_e32 v33, 2, v33
	v_mov_b32_e32 v33, v32
	s_nop 1
	v_permlane32_swap_b32_e32 v33, v32
	s_nop 1
	s_waitcnt lgkmcnt(0)
	v_add_f32_e32 v32, v32, v33
	v_fmamk_f32 v32, v32, 0x3c800000, v193
	v_mul_f32_e32 v33, 0x4b800000, v32
	v_cmp_gt_f32_e32 vcc, s35, v32
	s_nop 1
	v_cndmask_b32_e32 v32, v32, v33, vcc
	v_rsq_f32_e32 v32, v32
	s_nop 0
	v_mul_f32_e32 v33, 0x45800000, v32
	v_cndmask_b32_e32 v46, v32, v33, vcc
	v_pk_mul_f32 v[28:29], v[28:29], v[46:47] op_sel_hi:[1,0]
	v_pk_mul_f32 v[24:25], v[24:25], v[46:47] op_sel_hi:[1,0]
	v_pk_mul_f32 v[20:21], v[20:21], v[46:47] op_sel_hi:[1,0]
	v_pk_mul_f32 v[16:17], v[16:17], v[46:47] op_sel_hi:[1,0]
	v_pk_mul_f32 v[32:33], v[186:187], v[28:29]
	v_pk_mul_f32 v[28:29], v[30:31], v[46:47] op_sel_hi:[1,0]
	v_pk_mul_f32 v[36:37], v[188:189], v[24:25]
	v_pk_mul_f32 v[24:25], v[26:27], v[46:47] op_sel_hi:[1,0]
	v_pk_mul_f32 v[40:41], v[174:175], v[20:21]
	v_pk_mul_f32 v[20:21], v[22:23], v[46:47] op_sel_hi:[1,0]
	v_pk_mul_f32 v[44:45], v[178:179], v[16:17]
	v_pk_mul_f32 v[16:17], v[18:19], v[46:47] op_sel_hi:[1,0]
	v_pk_mul_f32 v[34:35], v[182:183], v[28:29]
	v_pk_mul_f32 v[38:39], v[184:185], v[24:25]
	v_pk_mul_f32 v[42:43], v[176:177], v[20:21]
	v_pk_mul_f32 v[46:47], v[180:181], v[16:17]

;     __device__ __forceinline__ void operator()(const f32x4 (&acc)[2][2][4][2], const pg8::Unit& u, int wr, int wc, int fr, int fq) const {
;     ...
;                 if (type == 2 || type == 3) {
;                     float ss = 0.f;
; #pragma unroll
;                     for (int bj = 0; bj < 2; ++bj)
; #pragma unroll
;                         for (int e = 0; e < 8; ++e) ss += v[bj][e] * v[bj][e];
;                     ss += __shfl_xor(ss, 16); ss += __shfl_xor(ss, 32);
;                     const float rs = rsqrtf(ss * (1.f / 64.f) + NORM_EPS);
; #pragma unroll
;                     for (int bj = 0; bj < 2; ++bj)
; #pragma unroll
;                         for (int e = 0; e < 8; ++e) v[bj][e] = v[bj][e] * rs * gg[bj][e];
.LBB0_517:
	v_mul_f32_e32 v20, v13, v13
	v_fmac_f32_e32 v20, v12, v12
	v_fmac_f32_e32 v20, v14, v14
	v_fmac_f32_e32 v20, v15, v15
	v_fmac_f32_e32 v20, v8, v8
	v_fmac_f32_e32 v20, v9, v9
	v_fmac_f32_e32 v20, v10, v10
	v_fmac_f32_e32 v20, v11, v11
	v_pk_mul_f32 v[18:19], v[4:5], v[4:5]
	v_pk_mul_f32 v[16:17], v[6:7], v[6:7]
	v_add_f32_e32 v18, v20, v18
	v_add_f32_e32 v18, v19, v18
	v_add_f32_e32 v16, v16, v18
	v_add_f32_e32 v20, v17, v16
	v_pk_mul_f32 v[18:19], v[0:1], v[0:1]
	v_pk_mul_f32 v[16:17], v[2:3], v[2:3]
	v_add_f32_e32 v18, v18, v20
	v_add_f32_e32 v18, v19, v18
	v_add_f32_e32 v16, v16, v18
	v_and_b32_e32 v18, 64, v195
	v_add_f32_e32 v16, v17, v16
	v_xor_b32_e32 v17, 16, v195
	v_add_u32_e32 v18, 64, v18
	v_cmp_lt_i32_e32 vcc, v17, v18
	s_nop 1
	v_cndmask_b32_e32 v17, v195, v17, vcc
	v_lshlrev_b32_e32 v17, 2, v17
	v_mov_b32_e32 v17, v16
	s_nop 1
	v_permlane16_swap_b32_e32 v17, v16
	s_nop 1
	s_waitcnt lgkmcnt(0)
	v_add_f32_e32 v16, v16, v17
	v_xor_b32_e32 v17, 32, v195
	v_cmp_lt_i32_e32 vcc, v17, v18
	s_nop 1
	v_cndmask_b32_e32 v17, v195, v17, vcc
	v_lshlrev_b32_e32 v17, 2, v17
	v_mov_b32_e32 v17, v16
	s_nop 1
	v_permlane32_swap_b32_e32 v17, v16
	s_nop 1
	s_waitcnt lgkmcnt(0)
	v_add_f32_e32 v16, v16, v17
	v_fmamk_f32 v16, v16, 0x3c800000, v193
	v_mul_f32_e32 v17, 0x4b800000, v16
	v_cmp_gt_f32_e32 vcc, s35, v16
	s_nop 1
	v_cndmask_b32_e32 v16, v16, v17, vcc
	v_rsq_f32_e32 v16, v16
	s_nop 0
	v_mul_f32_e32 v17, 0x45800000, v16
	v_cndmask_b32_e32 v30, v16, v17, vcc
	v_pk_mul_f32 v[12:13], v[12:13], v[30:31] op_sel_hi:[1,0]
	v_pk_mul_f32 v[8:9], v[8:9], v[30:31] op_sel_hi:[1,0]
	v_pk_mul_f32 v[4:5], v[4:5], v[30:31] op_sel_hi:[1,0]
	v_pk_mul_f32 v[0:1], v[0:1], v[30:31] op_sel_hi:[1,0]
	v_pk_mul_f32 v[16:17], v[186:187], v[12:13]
	v_pk_mul_f32 v[12:13], v[14:15], v[30:31] op_sel_hi:[1,0]
	v_pk_mul_f32 v[20:21], v[188:189], v[8:9]
	v_pk_mul_f32 v[8:9], v[10:11], v[30:31] op_sel_hi:[1,0]
	v_pk_mul_f32 v[24:25], v[174:175], v[4:5]
	v_pk_mul_f32 v[4:5], v[6:7], v[30:31] op_sel_hi:[1,0]
	v_pk_mul_f32 v[28:29], v[178:179], v[0:1]
	v_pk_mul_f32 v[0:1], v[2:3], v[30:31] op_sel_hi:[1,0]
	v_pk_mul_f32 v[18:19], v[182:183], v[12:13]
	v_pk_mul_f32 v[22:23], v[184:185], v[8:9]
	v_pk_mul_f32 v[26:27], v[176:177], v[4:5]
	v_pk_mul_f32 v[30:31], v[180:181], v[0:1]
